# GEMM K-loop heads (in, merge, out, up, down) aligned to 64 bytes with .p2align 6; otherwise v20
# speedup vs baseline: 1.0154x; 1.0033x over previous
.LBB0_128:
	s_ashr_i32 s49, s48, 31
	s_lshl_b64 s[4:5], s[48:49], 19
	s_add_u32 s52, s16, s4
	s_addc_u32 s53, s17, s5
	s_and_b64 s[4:5], s[6:7], exec
	s_cselect_b32 s11, s53, s15
	s_cselect_b32 s13, s52, s14
	s_ashr_i32 s51, s50, 31
	s_lshl_b64 s[4:5], s[50:51], 19
	s_add_u32 s54, s18, s4
	s_addc_u32 s55, s19, s5
	s_and_b64 s[4:5], s[6:7], exec
	s_cselect_b32 s22, s55, s9
	s_cselect_b32 s49, s54, s8
	s_add_u32 s51, s8, 0x100
	s_addc_u32 s58, s9, 0
	s_add_u32 s8, s14, 0x40080
	v_mov_b32_e32 v0, 0
	s_addc_u32 s9, s15, 0
	s_mov_b32 s59, -2
	s_waitcnt lgkmcnt(0)
	v_mov_b32_e32 v1, v0
	v_mov_b32_e32 v2, v0
	v_mov_b32_e32 v3, v0
	v_mov_b32_e32 v4, v0
	v_mov_b32_e32 v5, v0
	v_mov_b32_e32 v6, v0
	v_mov_b32_e32 v7, v0
	v_mov_b32_e32 v16, v0
	v_mov_b32_e32 v17, v0
	v_mov_b32_e32 v18, v0
	v_mov_b32_e32 v19, v0
	v_mov_b32_e32 v20, v0
	v_mov_b32_e32 v21, v0
	v_mov_b32_e32 v22, v0
	v_mov_b32_e32 v23, v0
	v_mov_b32_e32 v32, v0
	v_mov_b32_e32 v33, v0
	v_mov_b32_e32 v34, v0
	v_mov_b32_e32 v35, v0
	v_mov_b32_e32 v36, v0
	v_mov_b32_e32 v37, v0
	v_mov_b32_e32 v38, v0
	v_mov_b32_e32 v39, v0
	v_mov_b32_e32 v48, v0
	v_mov_b32_e32 v49, v0
	v_mov_b32_e32 v50, v0
	v_mov_b32_e32 v51, v0
	v_mov_b32_e32 v52, v0
	v_mov_b32_e32 v53, v0
	v_mov_b32_e32 v54, v0
	v_mov_b32_e32 v55, v0
	v_mov_b32_e32 v8, v0
	v_mov_b32_e32 v9, v0
	v_mov_b32_e32 v10, v0
	v_mov_b32_e32 v11, v0
	v_mov_b32_e32 v12, v0
	v_mov_b32_e32 v13, v0
	v_mov_b32_e32 v14, v0
	v_mov_b32_e32 v15, v0
	v_mov_b32_e32 v24, v0
	v_mov_b32_e32 v25, v0
	v_mov_b32_e32 v26, v0
	v_mov_b32_e32 v27, v0
	v_mov_b32_e32 v28, v0
	v_mov_b32_e32 v29, v0
	v_mov_b32_e32 v30, v0
	v_mov_b32_e32 v31, v0
	v_mov_b32_e32 v40, v0
	v_mov_b32_e32 v41, v0
	v_mov_b32_e32 v42, v0
	v_mov_b32_e32 v43, v0
	v_mov_b32_e32 v44, v0
	v_mov_b32_e32 v45, v0
	v_mov_b32_e32 v46, v0
	v_mov_b32_e32 v47, v0
	v_mov_b32_e32 v56, v0
	v_mov_b32_e32 v57, v0
	v_mov_b32_e32 v58, v0
	v_mov_b32_e32 v59, v0
	v_mov_b32_e32 v60, v0
	v_mov_b32_e32 v61, v0
	v_mov_b32_e32 v62, v0
	v_mov_b32_e32 v63, v0
	v_mov_b32_e32 v64, v0
	v_mov_b32_e32 v65, v0
	v_mov_b32_e32 v66, v0
	v_mov_b32_e32 v67, v0
	v_mov_b32_e32 v68, v0
	v_mov_b32_e32 v69, v0
	v_mov_b32_e32 v70, v0
	v_mov_b32_e32 v71, v0
	v_mov_b32_e32 v80, v0
	v_mov_b32_e32 v81, v0
	v_mov_b32_e32 v82, v0
	v_mov_b32_e32 v83, v0
	v_mov_b32_e32 v84, v0
	v_mov_b32_e32 v85, v0
	v_mov_b32_e32 v86, v0
	v_mov_b32_e32 v87, v0
	v_mov_b32_e32 v96, v0
	v_mov_b32_e32 v97, v0
	v_mov_b32_e32 v98, v0
	v_mov_b32_e32 v99, v0
	v_mov_b32_e32 v100, v0
	v_mov_b32_e32 v101, v0
	v_mov_b32_e32 v102, v0
	v_mov_b32_e32 v103, v0
	v_mov_b32_e32 v112, v0
	v_mov_b32_e32 v113, v0
	v_mov_b32_e32 v114, v0
	v_mov_b32_e32 v115, v0
	v_mov_b32_e32 v116, v0
	v_mov_b32_e32 v117, v0
	v_mov_b32_e32 v118, v0
	v_mov_b32_e32 v119, v0
	v_mov_b32_e32 v72, v0
	v_mov_b32_e32 v73, v0
	v_mov_b32_e32 v74, v0
	v_mov_b32_e32 v75, v0
	v_mov_b32_e32 v76, v0
	v_mov_b32_e32 v77, v0
	v_mov_b32_e32 v78, v0
	v_mov_b32_e32 v79, v0
	v_mov_b32_e32 v88, v0
	v_mov_b32_e32 v89, v0
	v_mov_b32_e32 v90, v0
	v_mov_b32_e32 v91, v0
	v_mov_b32_e32 v92, v0
	v_mov_b32_e32 v93, v0
	v_mov_b32_e32 v94, v0
	v_mov_b32_e32 v95, v0
	v_mov_b32_e32 v104, v0
	v_mov_b32_e32 v105, v0
	v_mov_b32_e32 v106, v0
	v_mov_b32_e32 v107, v0
	v_mov_b32_e32 v108, v0
	v_mov_b32_e32 v109, v0
	v_mov_b32_e32 v110, v0
	v_mov_b32_e32 v111, v0
	v_mov_b32_e32 v120, v0
	v_mov_b32_e32 v121, v0
	v_mov_b32_e32 v122, v0
	v_mov_b32_e32 v123, v0
	v_mov_b32_e32 v124, v0
	v_mov_b32_e32 v125, v0
	v_mov_b32_e32 v126, v0
	v_mov_b32_e32 v127, v0
	.p2align	6

.LBB0_586:
	s_add_i32 s27, s67, -2
	s_add_u32 s68, s10, 0x100
	s_addc_u32 s69, s11, 0
	s_add_u32 s8, s34, 0x1a0080
	s_addc_u32 s9, s35, 0
	s_mov_b32 s4, 0
	.p2align	6

.LBB0_753:
	s_ashr_i32 s23, s22, 31
	s_lshl_b64 s[4:5], s[22:23], 19
	s_add_u32 s26, s35, s4
	s_addc_u32 s27, s36, s5
	s_and_b64 s[4:5], s[8:9], exec
	s_cselect_b32 s23, s27, s29
	s_cselect_b32 s64, s26, s28
	s_add_u32 s65, s28, 0x100
	s_addc_u32 s66, s29, 0
	s_add_u32 s8, s30, 0x1a0080
	v_mov_b32_e32 v0, 0
	s_addc_u32 s9, s31, 0
	s_mov_b32 s67, -2
	v_mov_b32_e32 v1, v0
	v_mov_b32_e32 v2, v0
	v_mov_b32_e32 v3, v0
	v_mov_b32_e32 v4, v0
	v_mov_b32_e32 v5, v0
	v_mov_b32_e32 v6, v0
	v_mov_b32_e32 v7, v0
	v_mov_b32_e32 v12, v0
	v_mov_b32_e32 v13, v0
	v_mov_b32_e32 v14, v0
	v_mov_b32_e32 v15, v0
	v_mov_b32_e32 v20, v0
	v_mov_b32_e32 v21, v0
	v_mov_b32_e32 v22, v0
	v_mov_b32_e32 v23, v0
	v_mov_b32_e32 v28, v0
	v_mov_b32_e32 v29, v0
	v_mov_b32_e32 v30, v0
	v_mov_b32_e32 v31, v0
	v_mov_b32_e32 v36, v0
	v_mov_b32_e32 v37, v0
	v_mov_b32_e32 v38, v0
	v_mov_b32_e32 v39, v0
	v_mov_b32_e32 v44, v0
	v_mov_b32_e32 v45, v0
	v_mov_b32_e32 v46, v0
	v_mov_b32_e32 v47, v0
	v_mov_b32_e32 v52, v0
	v_mov_b32_e32 v53, v0
	v_mov_b32_e32 v54, v0
	v_mov_b32_e32 v55, v0
	v_mov_b32_e32 v8, v0
	v_mov_b32_e32 v9, v0
	v_mov_b32_e32 v10, v0
	v_mov_b32_e32 v11, v0
	v_mov_b32_e32 v16, v0
	v_mov_b32_e32 v17, v0
	v_mov_b32_e32 v18, v0
	v_mov_b32_e32 v19, v0
	v_mov_b32_e32 v24, v0
	v_mov_b32_e32 v25, v0
	v_mov_b32_e32 v26, v0
	v_mov_b32_e32 v27, v0
	v_mov_b32_e32 v32, v0
	v_mov_b32_e32 v33, v0
	v_mov_b32_e32 v34, v0
	v_mov_b32_e32 v35, v0
	v_mov_b32_e32 v40, v0
	v_mov_b32_e32 v41, v0
	v_mov_b32_e32 v42, v0
	v_mov_b32_e32 v43, v0
	v_mov_b32_e32 v48, v0
	v_mov_b32_e32 v49, v0
	v_mov_b32_e32 v50, v0
	v_mov_b32_e32 v51, v0
	v_mov_b32_e32 v56, v0
	v_mov_b32_e32 v57, v0
	v_mov_b32_e32 v58, v0
	v_mov_b32_e32 v59, v0
	v_mov_b32_e32 v60, v0
	v_mov_b32_e32 v61, v0
	v_mov_b32_e32 v62, v0
	v_mov_b32_e32 v63, v0
	v_mov_b32_e32 v64, v0
	v_mov_b32_e32 v65, v0
	v_mov_b32_e32 v66, v0
	v_mov_b32_e32 v67, v0
	v_mov_b32_e32 v68, v0
	v_mov_b32_e32 v69, v0
	v_mov_b32_e32 v70, v0
	v_mov_b32_e32 v71, v0
	v_mov_b32_e32 v76, v0
	v_mov_b32_e32 v77, v0
	v_mov_b32_e32 v78, v0
	v_mov_b32_e32 v79, v0
	v_mov_b32_e32 v84, v0
	v_mov_b32_e32 v85, v0
	v_mov_b32_e32 v86, v0
	v_mov_b32_e32 v87, v0
	v_mov_b32_e32 v92, v0
	v_mov_b32_e32 v93, v0
	v_mov_b32_e32 v94, v0
	v_mov_b32_e32 v95, v0
	v_mov_b32_e32 v100, v0
	v_mov_b32_e32 v101, v0
	v_mov_b32_e32 v102, v0
	v_mov_b32_e32 v103, v0
	v_mov_b32_e32 v104, v0
	v_mov_b32_e32 v105, v0
	v_mov_b32_e32 v106, v0
	v_mov_b32_e32 v107, v0
	v_mov_b32_e32 v108, v0
	v_mov_b32_e32 v109, v0
	v_mov_b32_e32 v110, v0
	v_mov_b32_e32 v111, v0
	v_mov_b32_e32 v72, v0
	v_mov_b32_e32 v73, v0
	v_mov_b32_e32 v74, v0
	v_mov_b32_e32 v75, v0
	v_mov_b32_e32 v80, v0
	v_mov_b32_e32 v81, v0
	v_mov_b32_e32 v82, v0
	v_mov_b32_e32 v83, v0
	v_mov_b32_e32 v88, v0
	v_mov_b32_e32 v89, v0
	v_mov_b32_e32 v90, v0
	v_mov_b32_e32 v91, v0
	v_mov_b32_e32 v96, v0
	v_mov_b32_e32 v97, v0
	v_mov_b32_e32 v98, v0
	v_mov_b32_e32 v99, v0
	v_mov_b32_e32 v112, v0
	v_mov_b32_e32 v113, v0
	v_mov_b32_e32 v114, v0
	v_mov_b32_e32 v115, v0
	v_mov_b32_e32 v116, v0
	v_mov_b32_e32 v117, v0
	v_mov_b32_e32 v118, v0
	v_mov_b32_e32 v119, v0
	v_mov_b32_e32 v120, v0
	v_mov_b32_e32 v121, v0
	v_mov_b32_e32 v122, v0
	v_mov_b32_e32 v123, v0
	v_mov_b32_e32 v124, v0
	v_mov_b32_e32 v125, v0
	v_mov_b32_e32 v126, v0
	v_mov_b32_e32 v127, v0
	.p2align	6

.LBB0_874:
	s_ashr_i32 s21, s20, 31
	s_lshl_b64 s[4:5], s[20:21], 19
	s_add_u32 s22, s3, s4
	s_addc_u32 s23, s36, s5
	s_and_b64 s[4:5], s[6:7], exec
	s_cselect_b32 s21, s23, s31
	s_cselect_b32 s63, s22, s30
	s_ashr_i32 s19, s18, 31
	s_lshl_b64 s[4:5], s[18:19], 19
	s_add_u32 s24, s37, s4
	s_addc_u32 s25, s39, s5
	s_and_b64 s[4:5], s[6:7], exec
	s_cselect_b32 s19, s25, s29
	s_cselect_b32 s64, s24, s28
	s_add_u32 s65, s28, 0x100
	s_addc_u32 s66, s29, 0
	s_add_u32 s28, s30, 0x40080
	v_mov_b32_e32 v0, 0
	s_addc_u32 s29, s31, 0
	s_mov_b32 s67, -2
	v_mov_b32_e32 v1, v0
	v_mov_b32_e32 v2, v0
	v_mov_b32_e32 v3, v0
	v_mov_b32_e32 v4, v0
	v_mov_b32_e32 v5, v0
	v_mov_b32_e32 v6, v0
	v_mov_b32_e32 v7, v0
	v_mov_b32_e32 v8, v0
	v_mov_b32_e32 v9, v0
	v_mov_b32_e32 v10, v0
	v_mov_b32_e32 v11, v0
	v_mov_b32_e32 v16, v0
	v_mov_b32_e32 v17, v0
	v_mov_b32_e32 v18, v0
	v_mov_b32_e32 v19, v0
	v_mov_b32_e32 v24, v0
	v_mov_b32_e32 v25, v0
	v_mov_b32_e32 v26, v0
	v_mov_b32_e32 v27, v0
	v_mov_b32_e32 v32, v0
	v_mov_b32_e32 v33, v0
	v_mov_b32_e32 v34, v0
	v_mov_b32_e32 v35, v0
	v_mov_b32_e32 v40, v0
	v_mov_b32_e32 v41, v0
	v_mov_b32_e32 v42, v0
	v_mov_b32_e32 v43, v0
	v_mov_b32_e32 v48, v0
	v_mov_b32_e32 v49, v0
	v_mov_b32_e32 v50, v0
	v_mov_b32_e32 v51, v0
	v_mov_b32_e32 v12, v0
	v_mov_b32_e32 v13, v0
	v_mov_b32_e32 v14, v0
	v_mov_b32_e32 v15, v0
	v_mov_b32_e32 v20, v0
	v_mov_b32_e32 v21, v0
	v_mov_b32_e32 v22, v0
	v_mov_b32_e32 v23, v0
	v_mov_b32_e32 v28, v0
	v_mov_b32_e32 v29, v0
	v_mov_b32_e32 v30, v0
	v_mov_b32_e32 v31, v0
	v_mov_b32_e32 v36, v0
	v_mov_b32_e32 v37, v0
	v_mov_b32_e32 v38, v0
	v_mov_b32_e32 v39, v0
	v_mov_b32_e32 v44, v0
	v_mov_b32_e32 v45, v0
	v_mov_b32_e32 v46, v0
	v_mov_b32_e32 v47, v0
	v_mov_b32_e32 v52, v0
	v_mov_b32_e32 v53, v0
	v_mov_b32_e32 v54, v0
	v_mov_b32_e32 v55, v0
	v_mov_b32_e32 v56, v0
	v_mov_b32_e32 v57, v0
	v_mov_b32_e32 v58, v0
	v_mov_b32_e32 v59, v0
	v_mov_b32_e32 v60, v0
	v_mov_b32_e32 v61, v0
	v_mov_b32_e32 v62, v0
	v_mov_b32_e32 v63, v0
	v_mov_b32_e32 v64, v0
	v_mov_b32_e32 v65, v0
	v_mov_b32_e32 v66, v0
	v_mov_b32_e32 v67, v0
	v_mov_b32_e32 v68, v0
	v_mov_b32_e32 v69, v0
	v_mov_b32_e32 v70, v0
	v_mov_b32_e32 v71, v0
	v_mov_b32_e32 v72, v0
	v_mov_b32_e32 v73, v0
	v_mov_b32_e32 v74, v0
	v_mov_b32_e32 v75, v0
	v_mov_b32_e32 v80, v0
	v_mov_b32_e32 v81, v0
	v_mov_b32_e32 v82, v0
	v_mov_b32_e32 v83, v0
	v_mov_b32_e32 v88, v0
	v_mov_b32_e32 v89, v0
	v_mov_b32_e32 v90, v0
	v_mov_b32_e32 v91, v0
	v_mov_b32_e32 v96, v0
	v_mov_b32_e32 v97, v0
	v_mov_b32_e32 v98, v0
	v_mov_b32_e32 v99, v0
	v_mov_b32_e32 v104, v0
	v_mov_b32_e32 v105, v0
	v_mov_b32_e32 v106, v0
	v_mov_b32_e32 v107, v0
	v_mov_b32_e32 v112, v0
	v_mov_b32_e32 v113, v0
	v_mov_b32_e32 v114, v0
	v_mov_b32_e32 v115, v0
	v_mov_b32_e32 v76, v0
	v_mov_b32_e32 v77, v0
	v_mov_b32_e32 v78, v0
	v_mov_b32_e32 v79, v0
	v_mov_b32_e32 v84, v0
	v_mov_b32_e32 v85, v0
	v_mov_b32_e32 v86, v0
	v_mov_b32_e32 v87, v0
	v_mov_b32_e32 v92, v0
	v_mov_b32_e32 v93, v0
	v_mov_b32_e32 v94, v0
	v_mov_b32_e32 v95, v0
	v_mov_b32_e32 v100, v0
	v_mov_b32_e32 v101, v0
	v_mov_b32_e32 v102, v0
	v_mov_b32_e32 v103, v0
	v_mov_b32_e32 v108, v0
	v_mov_b32_e32 v109, v0
	v_mov_b32_e32 v110, v0
	v_mov_b32_e32 v111, v0
	v_mov_b32_e32 v116, v0
	v_mov_b32_e32 v117, v0
	v_mov_b32_e32 v118, v0
	v_mov_b32_e32 v119, v0
	v_mov_b32_e32 v120, v0
	v_mov_b32_e32 v121, v0
	v_mov_b32_e32 v122, v0
	v_mov_b32_e32 v123, v0
	v_mov_b32_e32 v124, v0
	v_mov_b32_e32 v125, v0
	v_mov_b32_e32 v126, v0
	v_mov_b32_e32 v127, v0
	.p2align	6

.LBB0_1042:
	s_add_u32 s63, s24, 0x100
	s_addc_u32 s64, s25, 0
	s_add_u32 s24, s26, 0xb0080
	v_mov_b32_e32 v0, 0
	s_addc_u32 s25, s27, 0
	s_mov_b32 s65, -2
	v_mov_b32_e32 v1, v0
	v_mov_b32_e32 v2, v0
	v_mov_b32_e32 v3, v0
	v_mov_b32_e32 v4, v0
	v_mov_b32_e32 v5, v0
	v_mov_b32_e32 v6, v0
	v_mov_b32_e32 v7, v0
	v_mov_b32_e32 v16, v0
	v_mov_b32_e32 v17, v0
	v_mov_b32_e32 v18, v0
	v_mov_b32_e32 v19, v0
	v_mov_b32_e32 v20, v0
	v_mov_b32_e32 v21, v0
	v_mov_b32_e32 v22, v0
	v_mov_b32_e32 v23, v0
	v_mov_b32_e32 v32, v0
	v_mov_b32_e32 v33, v0
	v_mov_b32_e32 v34, v0
	v_mov_b32_e32 v35, v0
	v_mov_b32_e32 v36, v0
	v_mov_b32_e32 v37, v0
	v_mov_b32_e32 v38, v0
	v_mov_b32_e32 v39, v0
	v_mov_b32_e32 v48, v0
	v_mov_b32_e32 v49, v0
	v_mov_b32_e32 v50, v0
	v_mov_b32_e32 v51, v0
	v_mov_b32_e32 v52, v0
	v_mov_b32_e32 v53, v0
	v_mov_b32_e32 v54, v0
	v_mov_b32_e32 v55, v0
	v_mov_b32_e32 v8, v0
	v_mov_b32_e32 v9, v0
	v_mov_b32_e32 v10, v0
	v_mov_b32_e32 v11, v0
	v_mov_b32_e32 v12, v0
	v_mov_b32_e32 v13, v0
	v_mov_b32_e32 v14, v0
	v_mov_b32_e32 v15, v0
	v_mov_b32_e32 v24, v0
	v_mov_b32_e32 v25, v0
	v_mov_b32_e32 v26, v0
	v_mov_b32_e32 v27, v0
	v_mov_b32_e32 v28, v0
	v_mov_b32_e32 v29, v0
	v_mov_b32_e32 v30, v0
	v_mov_b32_e32 v31, v0
	v_mov_b32_e32 v40, v0
	v_mov_b32_e32 v41, v0
	v_mov_b32_e32 v42, v0
	v_mov_b32_e32 v43, v0
	v_mov_b32_e32 v44, v0
	v_mov_b32_e32 v45, v0
	v_mov_b32_e32 v46, v0
	v_mov_b32_e32 v47, v0
	v_mov_b32_e32 v56, v0
	v_mov_b32_e32 v57, v0
	v_mov_b32_e32 v58, v0
	v_mov_b32_e32 v59, v0
	v_mov_b32_e32 v60, v0
	v_mov_b32_e32 v61, v0
	v_mov_b32_e32 v62, v0
	v_mov_b32_e32 v63, v0
	v_mov_b32_e32 v64, v0
	v_mov_b32_e32 v65, v0
	v_mov_b32_e32 v66, v0
	v_mov_b32_e32 v67, v0
	v_mov_b32_e32 v68, v0
	v_mov_b32_e32 v69, v0
	v_mov_b32_e32 v70, v0
	v_mov_b32_e32 v71, v0
	v_mov_b32_e32 v80, v0
	v_mov_b32_e32 v81, v0
	v_mov_b32_e32 v82, v0
	v_mov_b32_e32 v83, v0
	v_mov_b32_e32 v84, v0
	v_mov_b32_e32 v85, v0
	v_mov_b32_e32 v86, v0
	v_mov_b32_e32 v87, v0
	v_mov_b32_e32 v96, v0
	v_mov_b32_e32 v97, v0
	v_mov_b32_e32 v98, v0
	v_mov_b32_e32 v99, v0
	v_mov_b32_e32 v100, v0
	v_mov_b32_e32 v101, v0
	v_mov_b32_e32 v102, v0
	v_mov_b32_e32 v103, v0
	v_mov_b32_e32 v112, v0
	v_mov_b32_e32 v113, v0
	v_mov_b32_e32 v114, v0
	v_mov_b32_e32 v115, v0
	v_mov_b32_e32 v116, v0
	v_mov_b32_e32 v117, v0
	v_mov_b32_e32 v118, v0
	v_mov_b32_e32 v119, v0
	v_mov_b32_e32 v72, v0
	v_mov_b32_e32 v73, v0
	v_mov_b32_e32 v74, v0
	v_mov_b32_e32 v75, v0
	v_mov_b32_e32 v76, v0
	v_mov_b32_e32 v77, v0
	v_mov_b32_e32 v78, v0
	v_mov_b32_e32 v79, v0
	v_mov_b32_e32 v88, v0
	v_mov_b32_e32 v89, v0
	v_mov_b32_e32 v90, v0
	v_mov_b32_e32 v91, v0
	v_mov_b32_e32 v92, v0
	v_mov_b32_e32 v93, v0
	v_mov_b32_e32 v94, v0
	v_mov_b32_e32 v95, v0
	v_mov_b32_e32 v104, v0
	v_mov_b32_e32 v105, v0
	v_mov_b32_e32 v106, v0
	v_mov_b32_e32 v107, v0
	v_mov_b32_e32 v108, v0
	v_mov_b32_e32 v109, v0
	v_mov_b32_e32 v110, v0
	v_mov_b32_e32 v111, v0
	v_mov_b32_e32 v120, v0
	v_mov_b32_e32 v121, v0
	v_mov_b32_e32 v122, v0
	v_mov_b32_e32 v123, v0
	v_mov_b32_e32 v124, v0
	v_mov_b32_e32 v125, v0
	v_mov_b32_e32 v126, v0
	v_mov_b32_e32 v127, v0
	.p2align	6
